# in-proj GEMM epilogue: the bf16 C stores issued non-temporal so they do not displace the operand tiles from L2; on v61
# baseline (speedup 1.0000x reference)
; __device__ __forceinline__ unsigned cvt_pk_bf16(float lo, float hi) { unsigned r; asm("v_cvt_pk_bf16_f32 %0, %1, %2" : "=v"(r) : "v"(lo), "v"(hi)); return r; }
;     __device__ __forceinline__ void operator()(const f32x4 (&acc)[2][2][4][2], const Unit& u, int wr, int wc, int fr, int fq) const {
;     ...
;         for (int ai = 0; ai < 2; ++ai)
; #pragma unroll
;             for (int m = 0; m < 4; ++m) { bf16_t* rowp = base + (size_t)(row0 + ai * HALF + m * 16) * ldc + col0;
; #pragma unroll
;                 for (int bj = 0; bj < 2; ++bj) { f32x4 v0 = acc[ai][bj][m][0] + bv[bj][0], v1 = acc[ai][bj][m][1] + bv[bj][1];
;                     if (ACT == 1) { f32x2 a = gelu_pk((f32x2){v0[0], v0[1]}), b = gelu_pk((f32x2){v0[2], v0[3]}), c = gelu_pk((f32x2){v1[0], v1[1]}), d = gelu_pk((f32x2){v1[2], v1[3]});
;                         v0 = (f32x4){a.x, a.y, b.x, b.y}; v1 = (f32x4){c.x, c.y, d.x, d.y}; }
;                     v0 = v0 * sc; v1 = v1 * sc; u32x4 w; w.x = cvt_pk_bf16(v0[0], v0[1]); w.y = cvt_pk_bf16(v0[2], v0[3]); w.z = cvt_pk_bf16(v1[0], v1[1]); w.w = cvt_pk_bf16(v1[2], v1[3]);
;                     *(u32x4*)(rowp + bj * HALF) = w; } }
.LBB0_343:
	v_lshl_add_u32 v150, s16, 8, v162
	v_lshl_or_b32 v148, s29, 8, v164
	v_ashrrev_i32_e32 v149, 31, v148
	v_ashrrev_i32_e32 v151, 31, v150
	v_lshl_add_u64 v[158:159], v[148:149], 1, v[138:139]
	v_lshlrev_b64 v[148:149], 14, v[150:151]
	v_lshl_add_u64 v[148:149], v[158:159], 0, v[148:149]
	v_pk_add_f32 v[126:127], v[126:127], 0 op_sel_hi:[1,0]
	v_pk_add_f32 v[124:125], v[124:125], 0 op_sel_hi:[1,0]
	v_pk_add_f32 v[160:161], v[122:123], 0 op_sel_hi:[1,0]
	v_pk_add_f32 v[122:123], v[120:121], 0 op_sel_hi:[1,0]
	v_cvt_pk_bf16_f32 v120, v124, v125
	v_cvt_pk_bf16_f32 v121, v126, v127
	v_pk_add_f32 v[116:117], v[116:117], 0 op_sel_hi:[1,0]
	v_cvt_pk_bf16_f32 v122, v122, v123
	v_cvt_pk_bf16_f32 v123, v160, v161
	global_store_dwordx4 v[148:149], v[120:123], off nt
	v_pk_add_f32 v[118:119], v[118:119], 0 op_sel_hi:[1,0]
	v_pk_add_f32 v[112:113], v[112:113], 0 op_sel_hi:[1,0]
	v_pk_add_f32 v[120:121], v[110:111], 0 op_sel_hi:[1,0]
	v_pk_add_f32 v[110:111], v[108:109], 0 op_sel_hi:[1,0]
	v_cvt_pk_bf16_f32 v108, v116, v117
	v_cvt_pk_bf16_f32 v109, v118, v119
	v_pk_add_f32 v[100:101], v[100:101], 0 op_sel_hi:[1,0]
	v_cvt_pk_bf16_f32 v110, v110, v111
	v_cvt_pk_bf16_f32 v111, v120, v121
	global_store_dwordx4 v[148:149], v[108:111], off offset:256 nt
	v_pk_add_f32 v[102:103], v[102:103], 0 op_sel_hi:[1,0]
	v_pk_add_f32 v[96:97], v[96:97], 0 op_sel_hi:[1,0]
	v_or_b32_e32 v108, 16, v150
	v_ashrrev_i32_e32 v109, 31, v108
	v_lshlrev_b64 v[108:109], 14, v[108:109]
	v_lshl_add_u64 v[108:109], v[158:159], 0, v[108:109]
	v_pk_add_f32 v[110:111], v[114:115], 0 op_sel_hi:[1,0]
	v_pk_add_f32 v[114:115], v[106:107], 0 op_sel_hi:[1,0]
	v_pk_add_f32 v[106:107], v[104:105], 0 op_sel_hi:[1,0]
	v_cvt_pk_bf16_f32 v104, v112, v113
	v_cvt_pk_bf16_f32 v105, v110, v111
	v_pk_add_f32 v[84:85], v[84:85], 0 op_sel_hi:[1,0]
	v_cvt_pk_bf16_f32 v106, v106, v107
	v_cvt_pk_bf16_f32 v107, v114, v115
	global_store_dwordx4 v[108:109], v[104:107], off nt
	v_pk_add_f32 v[86:87], v[86:87], 0 op_sel_hi:[1,0]
	v_pk_add_f32 v[80:81], v[80:81], 0 op_sel_hi:[1,0]
	v_pk_add_f32 v[104:105], v[94:95], 0 op_sel_hi:[1,0]
	v_pk_add_f32 v[94:95], v[92:93], 0 op_sel_hi:[1,0]
	v_cvt_pk_bf16_f32 v92, v100, v101
	v_cvt_pk_bf16_f32 v93, v102, v103
	v_pk_add_f32 v[60:61], v[60:61], 0 op_sel_hi:[1,0]
	v_cvt_pk_bf16_f32 v94, v94, v95
	v_cvt_pk_bf16_f32 v95, v104, v105
	global_store_dwordx4 v[108:109], v[92:95], off offset:256 nt
	s_mov_b32 s11, 0x200000
	v_pk_add_f32 v[70:71], v[70:71], 0 op_sel_hi:[1,0]
	v_or_b32_e32 v92, 32, v150
	v_ashrrev_i32_e32 v93, 31, v92
	v_lshlrev_b64 v[92:93], 14, v[92:93]
	v_lshl_add_u64 v[92:93], v[158:159], 0, v[92:93]
	v_pk_add_f32 v[94:95], v[98:99], 0 op_sel_hi:[1,0]
	v_pk_add_f32 v[98:99], v[90:91], 0 op_sel_hi:[1,0]
	v_pk_add_f32 v[90:91], v[88:89], 0 op_sel_hi:[1,0]
	v_cvt_pk_bf16_f32 v88, v96, v97
	v_cvt_pk_bf16_f32 v89, v94, v95
	v_pk_add_f32 v[68:69], v[68:69], 0 op_sel_hi:[1,0]
	v_cvt_pk_bf16_f32 v90, v90, v91
	v_cvt_pk_bf16_f32 v91, v98, v99
	global_store_dwordx4 v[92:93], v[88:91], off nt
	v_pk_add_f32 v[62:63], v[62:63], 0 op_sel_hi:[1,0]
	s_mov_b64 s[18:19], 0x200000
	v_pk_add_f32 v[88:89], v[78:79], 0 op_sel_hi:[1,0]
	v_pk_add_f32 v[78:79], v[76:77], 0 op_sel_hi:[1,0]
	v_cvt_pk_bf16_f32 v76, v84, v85
	v_cvt_pk_bf16_f32 v77, v86, v87
	v_pk_add_f32 v[54:55], v[54:55], 0 op_sel_hi:[1,0]
	v_cvt_pk_bf16_f32 v78, v78, v79
	v_cvt_pk_bf16_f32 v79, v88, v89
	global_store_dwordx4 v[92:93], v[76:79], off offset:256 nt
	v_pk_add_f32 v[52:53], v[52:53], 0 op_sel_hi:[1,0]
	v_pk_add_f32 v[48:49], v[48:49], 0 op_sel_hi:[1,0]
	v_or_b32_e32 v76, 48, v150
	v_ashrrev_i32_e32 v77, 31, v76
	v_lshlrev_b64 v[76:77], 14, v[76:77]
	v_lshl_add_u64 v[76:77], v[158:159], 0, v[76:77]
	v_pk_add_f32 v[78:79], v[82:83], 0 op_sel_hi:[1,0]
	v_pk_add_f32 v[82:83], v[74:75], 0 op_sel_hi:[1,0]
	v_pk_add_f32 v[74:75], v[72:73], 0 op_sel_hi:[1,0]
	v_cvt_pk_bf16_f32 v72, v80, v81
	v_cvt_pk_bf16_f32 v73, v78, v79
	v_pk_add_f32 v[38:39], v[38:39], 0 op_sel_hi:[1,0]
	v_cvt_pk_bf16_f32 v74, v74, v75
	v_cvt_pk_bf16_f32 v75, v82, v83
	global_store_dwordx4 v[76:77], v[72:75], off nt
; __device__ __forceinline__ unsigned cvt_pk_bf16(float lo, float hi) { unsigned r; asm("v_cvt_pk_bf16_f32 %0, %1, %2" : "=v"(r) : "v"(lo), "v"(hi)); return r; }
;     __device__ __forceinline__ void operator()(const f32x4 (&acc)[2][2][4][2], const Unit& u, int wr, int wc, int fr, int fq) const {
;     ...
;         for (int ai = 0; ai < 2; ++ai)
; #pragma unroll
;             for (int m = 0; m < 4; ++m) { bf16_t* rowp = base + (size_t)(row0 + ai * HALF + m * 16) * ldc + col0;
; #pragma unroll
;                 for (int bj = 0; bj < 2; ++bj) { f32x4 v0 = acc[ai][bj][m][0] + bv[bj][0], v1 = acc[ai][bj][m][1] + bv[bj][1];
;                     if (ACT == 1) { f32x2 a = gelu_pk((f32x2){v0[0], v0[1]}), b = gelu_pk((f32x2){v0[2], v0[3]}), c = gelu_pk((f32x2){v1[0], v1[1]}), d = gelu_pk((f32x2){v1[2], v1[3]});
;                         v0 = (f32x4){a.x, a.y, b.x, b.y}; v1 = (f32x4){c.x, c.y, d.x, d.y}; }
;                     v0 = v0 * sc; v1 = v1 * sc; u32x4 w; w.x = cvt_pk_bf16(v0[0], v0[1]); w.y = cvt_pk_bf16(v0[2], v0[3]); w.z = cvt_pk_bf16(v1[0], v1[1]); w.w = cvt_pk_bf16(v1[2], v1[3]);
;                     *(u32x4*)(rowp + bj * HALF) = w; } }
	v_pk_add_f32 v[36:37], v[36:37], 0 op_sel_hi:[1,0]
	v_pk_add_f32 v[32:33], v[32:33], 0 op_sel_hi:[1,0]
	v_pk_add_f32 v[72:73], v[66:67], 0 op_sel_hi:[1,0]
	v_pk_add_f32 v[66:67], v[64:65], 0 op_sel_hi:[1,0]
	v_cvt_pk_bf16_f32 v64, v68, v69
	v_cvt_pk_bf16_f32 v65, v70, v71
	v_pk_add_f32 v[22:23], v[22:23], 0 op_sel_hi:[1,0]
	v_cvt_pk_bf16_f32 v66, v66, v67
	v_cvt_pk_bf16_f32 v67, v72, v73
	global_store_dwordx4 v[76:77], v[64:67], off offset:256 nt
	v_pk_add_f32 v[20:21], v[20:21], 0 op_sel_hi:[1,0]
	v_pk_add_f32 v[16:17], v[16:17], 0 op_sel_hi:[1,0]
	v_pk_add_f32 v[66:67], v[58:59], 0 op_sel_hi:[1,0]
	v_pk_add_f32 v[58:59], v[56:57], 0 op_sel_hi:[1,0]
	v_cvt_pk_bf16_f32 v56, v60, v61
	v_add_co_u32_e32 v60, vcc, s11, v148
	v_cvt_pk_bf16_f32 v57, v62, v63
	v_cvt_pk_bf16_f32 v58, v58, v59
	v_cvt_pk_bf16_f32 v59, v66, v67
	v_lshl_add_u64 v[64:65], v[148:149], 0, s[18:19]
	s_nop 0
	v_addc_co_u32_e32 v61, vcc, 0, v149, vcc
	global_store_dwordx4 v[60:61], v[56:59], off nt
	s_mov_b32 s11, 0x240000
	s_mov_b64 s[18:19], 0x240000
	v_pk_add_f32 v[56:57], v[46:47], 0 op_sel_hi:[1,0]
	v_pk_add_f32 v[46:47], v[44:45], 0 op_sel_hi:[1,0]
	v_cvt_pk_bf16_f32 v44, v52, v53
	v_cvt_pk_bf16_f32 v45, v54, v55
	v_pk_add_f32 v[6:7], v[6:7], 0 op_sel_hi:[1,0]
	v_cvt_pk_bf16_f32 v46, v46, v47
	v_cvt_pk_bf16_f32 v47, v56, v57
	global_store_dwordx4 v[64:65], v[44:47], off offset:256 nt
	v_pk_add_f32 v[4:5], v[4:5], 0 op_sel_hi:[1,0]
	s_nop 0
	v_pk_add_f32 v[46:47], v[50:51], 0 op_sel_hi:[1,0]
	v_pk_add_f32 v[50:51], v[42:43], 0 op_sel_hi:[1,0]
	v_pk_add_f32 v[42:43], v[40:41], 0 op_sel_hi:[1,0]
	v_cvt_pk_bf16_f32 v41, v46, v47
	v_add_co_u32_e32 v46, vcc, s11, v148
	v_cvt_pk_bf16_f32 v40, v48, v49
	v_cvt_pk_bf16_f32 v42, v42, v43
	v_cvt_pk_bf16_f32 v43, v50, v51
	v_lshl_add_u64 v[44:45], v[148:149], 0, s[18:19]
	s_nop 0
	v_addc_co_u32_e32 v47, vcc, 0, v149, vcc
	global_store_dwordx4 v[46:47], v[40:43], off nt
	s_mov_b32 s11, 0x280000
	s_mov_b64 s[18:19], 0x280000
	v_pk_add_f32 v[40:41], v[30:31], 0 op_sel_hi:[1,0]
	v_pk_add_f32 v[30:31], v[28:29], 0 op_sel_hi:[1,0]
	v_cvt_pk_bf16_f32 v28, v36, v37
	v_cvt_pk_bf16_f32 v29, v38, v39
	s_nop 0
	v_cvt_pk_bf16_f32 v30, v30, v31
	v_cvt_pk_bf16_f32 v31, v40, v41
	global_store_dwordx4 v[44:45], v[28:31], off offset:256 nt
	s_nop 1
	v_pk_add_f32 v[30:31], v[34:35], 0 op_sel_hi:[1,0]
	v_pk_add_f32 v[34:35], v[26:27], 0 op_sel_hi:[1,0]
	v_pk_add_f32 v[26:27], v[24:25], 0 op_sel_hi:[1,0]
	v_cvt_pk_bf16_f32 v25, v30, v31
	v_add_co_u32_e32 v30, vcc, s11, v148
	v_cvt_pk_bf16_f32 v24, v32, v33
	v_cvt_pk_bf16_f32 v26, v26, v27
	v_cvt_pk_bf16_f32 v27, v34, v35
	v_lshl_add_u64 v[28:29], v[148:149], 0, s[18:19]
	s_nop 0
	v_addc_co_u32_e32 v31, vcc, 0, v149, vcc
	global_store_dwordx4 v[30:31], v[24:27], off nt
	s_mov_b32 s11, 0x2c0000
	s_mov_b64 s[18:19], 0x2c0000
	v_pk_add_f32 v[24:25], v[14:15], 0 op_sel_hi:[1,0]
	v_pk_add_f32 v[14:15], v[12:13], 0 op_sel_hi:[1,0]
	v_cvt_pk_bf16_f32 v12, v20, v21
	v_cvt_pk_bf16_f32 v13, v22, v23
	s_nop 0
	v_cvt_pk_bf16_f32 v14, v14, v15
	v_cvt_pk_bf16_f32 v15, v24, v25
	global_store_dwordx4 v[28:29], v[12:15], off offset:256 nt
	s_nop 1
	v_pk_add_f32 v[14:15], v[18:19], 0 op_sel_hi:[1,0]
	v_pk_add_f32 v[18:19], v[10:11], 0 op_sel_hi:[1,0]
	v_pk_add_f32 v[10:11], v[8:9], 0 op_sel_hi:[1,0]
	v_cvt_pk_bf16_f32 v9, v14, v15
	v_add_co_u32_e32 v14, vcc, s11, v148
	v_cvt_pk_bf16_f32 v8, v16, v17
	v_lshl_add_u64 v[12:13], v[148:149], 0, s[18:19]
	s_nop 0
	v_addc_co_u32_e32 v15, vcc, 0, v149, vcc
	v_cvt_pk_bf16_f32 v10, v10, v11
	v_cvt_pk_bf16_f32 v11, v18, v19
	global_store_dwordx4 v[14:15], v[8:11], off nt
	s_andn2_b64 vcc, exec, s[4:5]
	s_mov_b64 s[4:5], -1
	v_pk_add_f32 v[8:9], v[2:3], 0 op_sel_hi:[1,0]
	v_pk_add_f32 v[2:3], v[0:1], 0 op_sel_hi:[1,0]
	v_cvt_pk_bf16_f32 v0, v4, v5
	v_cvt_pk_bf16_f32 v1, v6, v7
	s_nop 0
	v_cvt_pk_bf16_f32 v2, v2, v3
	v_cvt_pk_bf16_f32 v3, v8, v9
	global_store_dwordx4 v[12:13], v[0:3], off offset:256 nt
	s_cbranch_vccnz .LBB0_332
	s_andn2_b64 vcc, exec, s[6:7]
	s_cbranch_vccnz .LBB0_331
	s_barrier
	s_branch .LBB0_331
